# sample indexer key-block loop: the seven further page-table entries loaded in one batch in the preheader; the block's MFMAs no longer wait for the next block's key rows
# speedup vs baseline: 1.0067x; 1.0059x over previous
.LBB0_1079:
	v_readlane_b32 s0, v252, 8
	v_readlane_b32 s1, v252, 9
	s_andn2_b64 vcc, exec, s[0:1]
	s_cbranch_vccnz .LBB0_1110
	v_or_b32_e32 v36, v36, v194
	v_readlane_b32 s6, v252, 35
	v_readlane_b32 s7, v252, 36
	v_lshlrev_b64 v[234:235], 2, v[34:35]
	s_nop 1
	v_lshl_add_u64 v[234:235], s[6:7], 0, v[234:235]
	global_load_dword v202, v[234:235], off
	global_load_dword v203, v[234:235], off offset:8
	global_load_dword v204, v[234:235], off offset:16
	global_load_dword v205, v[234:235], off offset:24
	global_load_dword v206, v[234:235], off offset:32
	global_load_dword v207, v[234:235], off offset:40
	global_load_dword v208, v[234:235], off offset:48
	s_waitcnt vmcnt(0)
	v_mul_f32_e32 v186, 0x3d3504f3, v37
	v_ashrrev_i32_e32 v37, 31, v36
	v_lshlrev_b64 v[36:37], 7, v[36:37]
	v_lshl_add_u64 v[188:189], v[106:107], 0, v[36:37]
	v_add_u32_e32 v36, v195, v1
	v_mad_i64_i32 v[190:191], s[0:1], v36, s59, v[182:183]
	v_readlane_b32 s0, v252, 35
	v_lshlrev_b64 v[34:35], 2, v[34:35]
	v_readlane_b32 s1, v252, 36
	v_mov_b32_e32 v187, v186
	s_mov_b32 s10, s90
	v_lshl_add_u64 v[192:193], s[0:1], 0, v[34:35]
	s_mov_b32 s11, s88
	s_branch .LBB0_1082
.LBB0_1081:
	s_or_b64 exec, exec, s[0:1]
	s_waitcnt vmcnt(0)
	s_add_i32 s6, s11, 8
	s_addk_i32 s10, 0x4000
	s_mov_b64 s[0:1], 0x400
	v_mov_b64_e32 v[2:3], v[58:59]
	v_mov_b64_e32 v[68:69], v[64:65]
	v_mov_b64_e32 v[6:7], v[50:51]
	v_mov_b64_e32 v[72:73], v[56:57]
	v_mov_b64_e32 v[10:11], v[42:43]
	v_mov_b64_e32 v[76:77], v[48:49]
	v_mov_b64_e32 v[14:15], v[34:35]
	v_mov_b64_e32 v[80:81], v[40:41]
	v_lshl_add_u64 v[190:191], v[190:191], 0, s[0:1]
	v_lshl_add_u64 v[192:193], v[192:193], 0, 8
	s_cmp_gt_u32 s11, 56
	v_mov_b64_e32 v[4:5], v[60:61]
	v_mov_b64_e32 v[66:67], v[62:63]
	v_mov_b64_e32 v[8:9], v[52:53]
	v_mov_b64_e32 v[70:71], v[54:55]
	v_mov_b64_e32 v[12:13], v[44:45]
	v_mov_b64_e32 v[74:75], v[46:47]
	v_mov_b64_e32 v[16:17], v[36:37]
	v_mov_b64_e32 v[78:79], v[38:39]
	s_mov_b32 s11, s6
	s_cbranch_scc1 .LBB0_1110
.LBB0_1082:
	s_cmp_gt_u32 s11, 55
	s_cbranch_scc1 .LBB0_1084
	v_mov_b32_e32 v34, v202
	v_mov_b32_e32 v202, v203
	v_mov_b32_e32 v203, v204
	v_mov_b32_e32 v204, v205
	v_mov_b32_e32 v205, v206
	v_mov_b32_e32 v206, v207
	v_mov_b32_e32 v207, v208
	s_and_b32 s0, s10, 0x1800
	v_or_b32_e32 v35, s0, v197
	v_lshlrev_b32_e32 v98, 2, v35
	v_readlane_b32 s36, v251, 6
	v_readlane_b32 s44, v251, 14
	v_readlane_b32 s45, v251, 15
	v_mov_b32_e32 v185, v99
	v_readlane_b32 s37, v251, 7
	v_readlane_b32 s38, v251, 8
	v_readlane_b32 s39, v251, 9
	v_readlane_b32 s40, v251, 10
	v_readlane_b32 s41, v251, 11
	v_readlane_b32 s42, v251, 12
	v_readlane_b32 s43, v251, 13
	v_readlane_b32 s46, v251, 16
	v_readlane_b32 s47, v251, 17
	v_readlane_b32 s48, v251, 18
	v_readlane_b32 s49, v251, 19
	v_readlane_b32 s50, v251, 20
	v_readlane_b32 s51, v251, 21
	s_nop 0
	v_ashrrev_i32_e32 v35, 31, v34
	v_lshlrev_b64 v[34:35], 15, v[34:35]
	v_lshl_add_u64 v[34:35], s[44:45], 0, v[34:35]
	v_lshl_add_u64 v[34:35], v[34:35], 0, v[98:99]
	v_lshl_add_u64 v[62:63], v[34:35], 0, v[184:185]
	global_load_dwordx4 v[34:37], v[62:63], off offset:16
	global_load_dwordx4 v[38:41], v[62:63], off
	global_load_dwordx4 v[42:45], v[62:63], off offset:80
	global_load_dwordx4 v[46:49], v[62:63], off offset:64
	global_load_dwordx4 v[50:53], v[62:63], off offset:144
	global_load_dwordx4 v[54:57], v[62:63], off offset:128
	global_load_dwordx4 v[58:61], v[62:63], off offset:208
	s_nop 0
	global_load_dwordx4 v[62:65], v[62:63], off offset:192

.Lis_nowait:
	v_mfma_f32_32x32x16_bf16 v[2:17], v[82:85], v[18:21], 0
	v_cmp_lt_i32_e32 vcc, 1, v196
	v_mfma_f32_32x32x16_bf16 v[2:17], v[86:89], v[22:25], v[2:17]
	v_mfma_f32_32x32x16_bf16 v[2:17], v[94:97], v[26:29], v[2:17]
	v_mfma_f32_32x32x16_bf16 v[2:17], v[90:93], v[30:33], v[2:17]
	s_nop 11
	v_max_f32_e32 v2, v2, v2
	v_max_f32_e32 v3, v3, v3
	v_max_f32_e32 v4, v4, v4
	v_max_f32_e32 v5, v5, v5
	v_max_f32_e32 v6, v6, v6
	v_max_f32_e32 v7, v7, v7
	v_max_f32_e32 v2, 0, v2
	v_max_f32_e32 v3, 0, v3
	v_max_f32_e32 v4, 0, v4
	v_max_f32_e32 v5, 0, v5
	v_max_f32_e32 v6, 0, v6
	v_max_f32_e32 v7, 0, v7
	v_pk_mul_f32 v[66:67], v[186:187], v[2:3]
	v_pk_mul_f32 v[68:69], v[186:187], v[4:5]
	v_pk_mul_f32 v[70:71], v[186:187], v[6:7]
	v_mov_b32_dpp v66, v66 quad_perm:[1,0,3,2] row_mask:0xf bank_mask:0xf bound_ctrl:1
	v_mov_b32_dpp v67, v67 quad_perm:[1,0,3,2] row_mask:0xf bank_mask:0xf bound_ctrl:1
	v_mov_b32_dpp v68, v68 quad_perm:[1,0,3,2] row_mask:0xf bank_mask:0xf bound_ctrl:1
	v_mov_b32_dpp v69, v69 quad_perm:[1,0,3,2] row_mask:0xf bank_mask:0xf bound_ctrl:1
	v_mov_b32_dpp v70, v70 quad_perm:[1,0,3,2] row_mask:0xf bank_mask:0xf bound_ctrl:1
	v_mov_b32_dpp v71, v71 quad_perm:[1,0,3,2] row_mask:0xf bank_mask:0xf bound_ctrl:1
	v_pk_fma_f32 v[2:3], v[186:187], v[2:3], v[66:67]
	v_pk_fma_f32 v[4:5], v[186:187], v[4:5], v[68:69]
	v_pk_fma_f32 v[6:7], v[186:187], v[6:7], v[70:71]
	v_max_f32_e32 v8, v8, v8
	v_max_f32_e32 v9, v9, v9
	v_max_f32_e32 v10, v10, v10
	v_max_f32_e32 v11, v11, v11
	v_max_f32_e32 v12, v12, v12
	v_max_f32_e32 v13, v13, v13
	v_max_f32_e32 v14, v14, v14
	v_max_f32_e32 v15, v15, v15
	v_max_f32_e32 v16, v16, v16
	v_max_f32_e32 v17, v17, v17
	v_mov_b32_dpp v66, v2 quad_perm:[2,3,0,1] row_mask:0xf bank_mask:0xf bound_ctrl:1
	v_mov_b32_dpp v67, v3 quad_perm:[2,3,0,1] row_mask:0xf bank_mask:0xf bound_ctrl:1
	v_mov_b32_dpp v68, v4 quad_perm:[2,3,0,1] row_mask:0xf bank_mask:0xf bound_ctrl:1
	v_mov_b32_dpp v69, v5 quad_perm:[2,3,0,1] row_mask:0xf bank_mask:0xf bound_ctrl:1
	v_mov_b32_dpp v70, v6 quad_perm:[2,3,0,1] row_mask:0xf bank_mask:0xf bound_ctrl:1
	v_mov_b32_dpp v71, v7 quad_perm:[2,3,0,1] row_mask:0xf bank_mask:0xf bound_ctrl:1
	v_max_f32_e32 v8, 0, v8
	v_max_f32_e32 v9, 0, v9
	v_max_f32_e32 v10, 0, v10
	v_max_f32_e32 v11, 0, v11
	v_max_f32_e32 v12, 0, v12
	v_max_f32_e32 v13, 0, v13
	v_max_f32_e32 v14, 0, v14
	v_max_f32_e32 v15, 0, v15
	v_max_f32_e32 v16, 0, v16
	v_max_f32_e32 v17, 0, v17
	v_pk_add_f32 v[2:3], v[2:3], v[66:67]
	v_pk_add_f32 v[4:5], v[4:5], v[68:69]
	v_pk_add_f32 v[66:67], v[6:7], v[70:71]
	v_pk_mul_f32 v[68:69], v[186:187], v[8:9]
	v_pk_mul_f32 v[70:71], v[186:187], v[10:11]
	v_pk_mul_f32 v[76:77], v[186:187], v[12:13]
	v_pk_mul_f32 v[78:79], v[186:187], v[14:15]
	v_pk_mul_f32 v[80:81], v[186:187], v[16:17]
	v_mov_b32_dpp v68, v68 quad_perm:[1,0,3,2] row_mask:0xf bank_mask:0xf bound_ctrl:1
	v_mov_b32_dpp v69, v69 quad_perm:[1,0,3,2] row_mask:0xf bank_mask:0xf bound_ctrl:1
	v_mov_b32_dpp v70, v70 quad_perm:[1,0,3,2] row_mask:0xf bank_mask:0xf bound_ctrl:1
	v_mov_b32_dpp v71, v71 quad_perm:[1,0,3,2] row_mask:0xf bank_mask:0xf bound_ctrl:1
	v_mov_b32_dpp v76, v76 quad_perm:[1,0,3,2] row_mask:0xf bank_mask:0xf bound_ctrl:1
	v_mov_b32_dpp v77, v77 quad_perm:[1,0,3,2] row_mask:0xf bank_mask:0xf bound_ctrl:1
	v_mov_b32_dpp v78, v78 quad_perm:[1,0,3,2] row_mask:0xf bank_mask:0xf bound_ctrl:1
	v_mov_b32_dpp v79, v79 quad_perm:[1,0,3,2] row_mask:0xf bank_mask:0xf bound_ctrl:1
	v_mov_b32_dpp v80, v80 quad_perm:[1,0,3,2] row_mask:0xf bank_mask:0xf bound_ctrl:1
	v_mov_b32_dpp v81, v81 quad_perm:[1,0,3,2] row_mask:0xf bank_mask:0xf bound_ctrl:1
	v_pk_fma_f32 v[8:9], v[186:187], v[8:9], v[68:69]
	v_pk_fma_f32 v[10:11], v[186:187], v[10:11], v[70:71]
	v_pk_fma_f32 v[12:13], v[186:187], v[12:13], v[76:77]
	v_pk_fma_f32 v[14:15], v[186:187], v[14:15], v[78:79]
	v_pk_fma_f32 v[16:17], v[186:187], v[16:17], v[80:81]
	v_mov_b32_dpp v68, v8 quad_perm:[2,3,0,1] row_mask:0xf bank_mask:0xf bound_ctrl:1
	v_mov_b32_dpp v69, v9 quad_perm:[2,3,0,1] row_mask:0xf bank_mask:0xf bound_ctrl:1
	v_mov_b32_dpp v70, v10 quad_perm:[2,3,0,1] row_mask:0xf bank_mask:0xf bound_ctrl:1
	v_mov_b32_dpp v71, v11 quad_perm:[2,3,0,1] row_mask:0xf bank_mask:0xf bound_ctrl:1
	v_mov_b32_dpp v76, v12 quad_perm:[2,3,0,1] row_mask:0xf bank_mask:0xf bound_ctrl:1
	v_mov_b32_dpp v77, v13 quad_perm:[2,3,0,1] row_mask:0xf bank_mask:0xf bound_ctrl:1
	v_mov_b32_dpp v78, v14 quad_perm:[2,3,0,1] row_mask:0xf bank_mask:0xf bound_ctrl:1
	v_mov_b32_dpp v79, v15 quad_perm:[2,3,0,1] row_mask:0xf bank_mask:0xf bound_ctrl:1
	v_mov_b32_dpp v80, v16 quad_perm:[2,3,0,1] row_mask:0xf bank_mask:0xf bound_ctrl:1
	v_mov_b32_dpp v81, v17 quad_perm:[2,3,0,1] row_mask:0xf bank_mask:0xf bound_ctrl:1
	v_mov_b32_dpp v72, v2 row_half_mirror row_mask:0xf bank_mask:0xf bound_ctrl:1
	v_mov_b32_dpp v73, v3 row_half_mirror row_mask:0xf bank_mask:0xf bound_ctrl:1
	v_mov_b32_dpp v74, v4 row_half_mirror row_mask:0xf bank_mask:0xf bound_ctrl:1
	v_mov_b32_dpp v75, v5 row_half_mirror row_mask:0xf bank_mask:0xf bound_ctrl:1
	v_pk_add_f32 v[68:69], v[8:9], v[68:69]
	v_pk_add_f32 v[70:71], v[10:11], v[70:71]
	v_pk_add_f32 v[76:77], v[12:13], v[76:77]
	v_pk_add_f32 v[14:15], v[14:15], v[78:79]
	v_pk_add_f32 v[16:17], v[16:17], v[80:81]
	v_mov_b32_dpp v6, v66 row_half_mirror row_mask:0xf bank_mask:0xf bound_ctrl:1
	v_mov_b32_dpp v7, v67 row_half_mirror row_mask:0xf bank_mask:0xf bound_ctrl:1
	v_mov_b32_dpp v8, v68 row_half_mirror row_mask:0xf bank_mask:0xf bound_ctrl:1
	v_mov_b32_dpp v9, v69 row_half_mirror row_mask:0xf bank_mask:0xf bound_ctrl:1
	v_mov_b32_dpp v10, v70 row_half_mirror row_mask:0xf bank_mask:0xf bound_ctrl:1
	v_mov_b32_dpp v11, v71 row_half_mirror row_mask:0xf bank_mask:0xf bound_ctrl:1
	v_mov_b32_dpp v12, v76 row_half_mirror row_mask:0xf bank_mask:0xf bound_ctrl:1
	v_mov_b32_dpp v13, v77 row_half_mirror row_mask:0xf bank_mask:0xf bound_ctrl:1
	v_mov_b32_dpp v78, v14 row_half_mirror row_mask:0xf bank_mask:0xf bound_ctrl:1
	v_mov_b32_dpp v79, v15 row_half_mirror row_mask:0xf bank_mask:0xf bound_ctrl:1
	v_mov_b32_dpp v80, v16 row_half_mirror row_mask:0xf bank_mask:0xf bound_ctrl:1
	v_mov_b32_dpp v81, v17 row_half_mirror row_mask:0xf bank_mask:0xf bound_ctrl:1
	v_pk_add_f32 v[4:5], v[4:5], v[74:75]
	v_pk_add_f32 v[2:3], v[2:3], v[72:73]
	s_and_saveexec_b64 s[0:1], vcc
	s_xor_b64 s[0:1], exec, s[0:1]
	s_cbranch_execz .LBB0_1105
	v_cmp_lt_i32_e32 vcc, 2, v196
	s_and_saveexec_b64 s[6:7], vcc
	s_xor_b64 s[6:7], exec, s[6:7]
	s_cbranch_execz .LBB0_1101
	v_cmp_eq_u32_e32 vcc, 3, v196
	s_and_saveexec_b64 s[8:9], vcc
	v_pk_add_f32 v[4:5], v[16:17], v[80:81]
	v_pk_add_f32 v[2:3], v[14:15], v[78:79]
	s_or_b64 exec, exec, s[8:9]
